# in-proj GEMM loop: S_A(0,0) LDS-DMA pieces issued in phase 3 instead of phase 2 (2/4/4/6 pieces, phase-2 wait vmcnt(6))
# speedup vs baseline: 1.0036x; 1.0036x over previous
; #define PG8_STAGE(bufoff, gbase, voff) do { _Pragma("unroll") for (int _i = 0; _i < 2; ++_i) \
;         __builtin_amdgcn_global_load_lds((const unsigned*)((const char*)(gbase) + (voff)[_i]), (LAS unsigned*)(lds + (bufoff) + ldsw + _i * 8192), 16, 0, 0); } while (0)
; #define PG8_LDA(dst, b, h) do { _Pragma("unroll") for (int m = 0; m < 4; ++m) _Pragma("unroll") for (int k = 0; k < 2; ++k) dst[m][k] = *(const LAS bf16x8*)(lds + PG8_SA(b, h) + aoff + m * 2048 + k * 1024); } while (0)
; #define PG8_LDB(dst, b, h) do { _Pragma("unroll") for (int n = 0; n < 2; ++n) _Pragma("unroll") for (int k = 0; k < 2; ++k) dst[n][k] = *(const LAS bf16x8*)(lds + PG8_SB(b, h) + boff + n * 2048 + k * 1024); } while (0)
; #define PG8_WAIT_V(n) asm volatile("s_waitcnt vmcnt(" #n ")" ::: "memory")
; #define PG8_WAIT_L(n) asm volatile("s_waitcnt lgkmcnt(" #n ")" ::: "memory")
; #define PG8_BAR __builtin_amdgcn_s_barrier()
; #define PG8_SCHED __builtin_amdgcn_sched_barrier(0)
; template <class Epi>
; __device__ __forceinline__ void gemm_phase(LAS unsigned char* lds, const Gemm g, const StaticOrder& S, const Epi& E, const int tid) {
;     ...
;         for (int t = 0; t < nt; t += 2) {
;             const bool last = (t == nt - 2);
;             const char* a1 = cA + (size_t)(t + 1) * kstep;
;             const char* a2 = last ? nA : cA + (size_t)(t + 2) * kstep; const char* b2 = last ? nB : cB + (size_t)(t + 2) * kstep;
;             const char* a3 = a2 + kstep; const char* b3 = b2 + kstep;
;             if constexpr (Epi::MID) { if (t == 16 || t == 32) { int fr_ = fr, fq_ = fq, wr_ = wr, wc_ = wc;
;                 asm volatile("" : "+v"(fr_), "+v"(fq_)); asm volatile("" : "+s"(wr_), "+s"(wc_));
;                 E.mid(acc, cur, t >> 4, wr_, wc_, fr_, fq_); PG8_WAIT_V(0); PG8_SCHED; } }
;             PG8_LDB(B0, 0, 0); PG8_LDB(B1, 0, 1); PG8_SCHED; PG8_LDA(At, 0, 0); PG8_STAGE(PG8_SA(1, 1), a1 + hstep, voffA);
;             PG8_WAIT_V(8); PG8_WAIT_L(0); PG8_BAR; PG8_MMA(0, 0, At, B0); PG8_MMA(0, 1, At, B1); PG8_BAR; PG8_SCHED;
;             PG8_LDA(At, 0, 1); PG8_STAGE(PG8_SB(0, 0), b2, voffB); PG8_STAGE(PG8_SB(0, 1), b2 + hstep, voffB); PG8_STAGE(PG8_SA(0, 0), a2, voffA);
;             PG8_WAIT_V(8); PG8_WAIT_L(0); PG8_BAR; PG8_MMA(1, 0, At, B0); PG8_MMA(1, 1, At, B1); PG8_BAR; PG8_SCHED;
.LBB0_214:
	s_add_u32 s21, s44, 0xfff80080
	s_addc_u32 s29, s45, -1
	s_add_i32 s31, 0, 0x10000
	s_cmp_eq_u32 s20, 28
	s_cselect_b32 s49, s2, s29
	s_cselect_b32 s48, s3, s21
	s_cselect_b32 s47, s4, s13
	s_cselect_b32 s46, s5, s10
	s_add_i32 s21, 0, 0x14000
	v_add_u32_e32 v140, s31, v187
	v_add_u32_e32 v156, s21, v187
	s_waitcnt lgkmcnt(0)
	ds_read_b128 v[128:131], v140
	ds_read_b128 v[132:135], v140 offset:1024
	ds_read_b128 v[136:139], v140 offset:2048
	ds_read_b128 v[140:143], v140 offset:3072
	ds_read_b128 v[144:147], v156
	ds_read_b128 v[148:151], v156 offset:1024
	ds_read_b128 v[152:155], v156 offset:2048
	ds_read_b128 v[156:159], v156 offset:3072
	v_lshl_add_u64 v[220:221], s[44:45], 0, v[200:201]
	s_add_i32 m0, s37, 0xc000
	ds_read_b128 v[160:163], v191
	ds_read_b128 v[164:167], v191 offset:1024
	ds_read_b128 v[168:171], v191 offset:2048
	ds_read_b128 v[172:175], v191 offset:3072
	ds_read_b128 v[204:207], v191 offset:4096
	ds_read_b128 v[208:211], v191 offset:5120
	ds_read_b128 v[212:215], v191 offset:6144
	ds_read_b128 v[216:219], v191 offset:7168
	global_load_lds_dwordx4 v[220:221], off
	v_lshl_add_u64 v[220:221], s[44:45], 0, v[202:203]
	s_add_i32 m0, s37, 0xe000
	s_nop 0
	global_load_lds_dwordx4 v[220:221], off
	s_waitcnt vmcnt(8)
	s_waitcnt lgkmcnt(0)
	s_barrier
	s_setprio 1
	s_waitcnt lgkmcnt(0)
	v_mfma_f32_16x16x32_bf16 v[124:127], v[128:131], v[160:163], v[124:127]
	v_mfma_f32_16x16x32_bf16 v[108:111], v[136:139], v[160:163], v[108:111]
	v_mfma_f32_16x16x32_bf16 v[116:119], v[128:131], v[168:171], v[116:119]
	v_mfma_f32_16x16x32_bf16 v[100:103], v[136:139], v[168:171], v[100:103]
	v_mfma_f32_16x16x32_bf16 v[92:95], v[128:131], v[204:207], v[92:95]
	v_mfma_f32_16x16x32_bf16 v[76:79], v[136:139], v[204:207], v[76:79]
	v_mfma_f32_16x16x32_bf16 v[84:87], v[128:131], v[212:215], v[84:87]
	v_mfma_f32_16x16x32_bf16 v[68:71], v[136:139], v[212:215], v[68:71]
	v_mfma_f32_16x16x32_bf16 v[124:127], v[132:135], v[164:167], v[124:127]
	v_mfma_f32_16x16x32_bf16 v[108:111], v[140:143], v[164:167], v[108:111]
	v_mfma_f32_16x16x32_bf16 v[116:119], v[132:135], v[172:175], v[116:119]
	v_mfma_f32_16x16x32_bf16 v[100:103], v[140:143], v[172:175], v[100:103]
	v_mfma_f32_16x16x32_bf16 v[92:95], v[132:135], v[208:211], v[92:95]
	v_mfma_f32_16x16x32_bf16 v[76:79], v[140:143], v[208:211], v[76:79]
	v_mfma_f32_16x16x32_bf16 v[84:87], v[132:135], v[216:219], v[84:87]
	v_mfma_f32_16x16x32_bf16 v[68:71], v[140:143], v[216:219], v[68:71]
	s_setprio 0
	s_setprio 1
	v_mfma_f32_16x16x32_bf16 v[120:123], v[144:147], v[160:163], v[120:123]
	v_mfma_f32_16x16x32_bf16 v[104:107], v[152:155], v[160:163], v[104:107]
	v_mfma_f32_16x16x32_bf16 v[112:115], v[144:147], v[168:171], v[112:115]
	v_mfma_f32_16x16x32_bf16 v[96:99], v[152:155], v[168:171], v[96:99]
	v_mfma_f32_16x16x32_bf16 v[88:91], v[144:147], v[204:207], v[88:91]
	v_mfma_f32_16x16x32_bf16 v[72:75], v[152:155], v[204:207], v[72:75]
	v_mfma_f32_16x16x32_bf16 v[80:83], v[144:147], v[212:215], v[80:83]
	v_mfma_f32_16x16x32_bf16 v[64:67], v[152:155], v[212:215], v[64:67]
	v_mfma_f32_16x16x32_bf16 v[120:123], v[148:151], v[164:167], v[120:123]
	v_mfma_f32_16x16x32_bf16 v[104:107], v[156:159], v[164:167], v[104:107]
	v_mfma_f32_16x16x32_bf16 v[112:115], v[148:151], v[172:175], v[112:115]
	v_mfma_f32_16x16x32_bf16 v[96:99], v[156:159], v[172:175], v[96:99]
	v_mfma_f32_16x16x32_bf16 v[88:91], v[148:151], v[208:211], v[88:91]
	v_mfma_f32_16x16x32_bf16 v[72:75], v[156:159], v[208:211], v[72:75]
	v_mfma_f32_16x16x32_bf16 v[80:83], v[148:151], v[216:219], v[80:83]
	v_mfma_f32_16x16x32_bf16 v[64:67], v[156:159], v[216:219], v[64:67]
	s_setprio 0
	s_barrier
	s_add_i32 s29, s31, s62
	v_lshl_add_u64 v[220:221], s[46:47], 0, v[194:195]
	s_mov_b32 m0, s29
	ds_read_b128 v[160:163], v191 offset:16384
	ds_read_b128 v[164:167], v191 offset:17408
	ds_read_b128 v[168:171], v191 offset:18432
	ds_read_b128 v[172:175], v191 offset:19456
	ds_read_b128 v[204:207], v191 offset:20480
	ds_read_b128 v[208:211], v191 offset:21504
	ds_read_b128 v[212:215], v191 offset:22528
	ds_read_b128 v[216:219], v191 offset:23552
	global_load_lds_dwordx4 v[220:221], off
	s_add_i32 m0, s29, 0x2000
	s_add_u32 s42, s46, 0x80000
	v_lshl_add_u64 v[222:223], s[46:47], 0, v[198:199]
	s_addc_u32 s43, s47, 0
	s_add_i32 s21, s21, s62
	global_load_lds_dwordx4 v[222:223], off
	v_lshl_add_u64 v[224:225], s[42:43], 0, v[194:195]
	s_mov_b32 m0, s21
	v_lshl_add_u64 v[238:239], s[48:49], 0, v[196:197]
	global_load_lds_dwordx4 v[224:225], off
	v_lshl_add_u64 v[224:225], s[42:43], 0, v[198:199]
	s_add_i32 m0, s21, 0x2000
	s_nop 0
	global_load_lds_dwordx4 v[224:225], off
	v_lshl_add_u64 v[224:225], s[48:49], 0, v[192:193]
	s_waitcnt vmcnt(6)
	s_waitcnt lgkmcnt(0)
	s_barrier
; #define PG8_STAGE(bufoff, gbase, voff) do { _Pragma("unroll") for (int _i = 0; _i < 2; ++_i) \
;         __builtin_amdgcn_global_load_lds((const unsigned*)((const char*)(gbase) + (voff)[_i]), (LAS unsigned*)(lds + (bufoff) + ldsw + _i * 8192), 16, 0, 0); } while (0)
; #define PG8_LDA(dst, b, h) do { _Pragma("unroll") for (int m = 0; m < 4; ++m) _Pragma("unroll") for (int k = 0; k < 2; ++k) dst[m][k] = *(const LAS bf16x8*)(lds + PG8_SA(b, h) + aoff + m * 2048 + k * 1024); } while (0)
; #define PG8_LDB(dst, b, h) do { _Pragma("unroll") for (int n = 0; n < 2; ++n) _Pragma("unroll") for (int k = 0; k < 2; ++k) dst[n][k] = *(const LAS bf16x8*)(lds + PG8_SB(b, h) + boff + n * 2048 + k * 1024); } while (0)
; #define PG8_MMA(ai, bj, At, Bt) do { __builtin_amdgcn_s_setprio(1); _Pragma("unroll") for (int m = 0; m < 4; ++m) _Pragma("unroll") for (int n = 0; n < 2; ++n) _Pragma("unroll") for (int k = 0; k < 2; ++k) \
;         acc[ai][bj][m][n] = __builtin_amdgcn_mfma_f32_16x16x32_bf16(Bt[n][k], At[m][k], acc[ai][bj][m][n], 0, 0, 0); __builtin_amdgcn_s_setprio(0); } while (0)
; #define PG8_WAIT_V(n) asm volatile("s_waitcnt vmcnt(" #n ")" ::: "memory")
; #define PG8_WAIT_L(n) asm volatile("s_waitcnt lgkmcnt(" #n ")" ::: "memory")
; #define PG8_BAR __builtin_amdgcn_s_barrier()
; #define PG8_SCHED __builtin_amdgcn_sched_barrier(0)
; template <class Epi>
; __device__ __forceinline__ void gemm_phase(LAS unsigned char* lds, const Gemm g, const StaticOrder& S, const Epi& E, const int tid) {
;     ...
;             PG8_WAIT_V(8); PG8_WAIT_L(0); PG8_BAR; PG8_MMA(1, 0, At, B0); PG8_MMA(1, 1, At, B1); PG8_BAR; PG8_SCHED;
;             PG8_LDB(B0, 1, 0); PG8_LDB(B1, 1, 1); PG8_SCHED; PG8_LDA(At, 1, 0); PG8_STAGE(PG8_SA(0, 1), a2 + hstep, voffA);
;             PG8_WAIT_V(8); PG8_WAIT_L(0); PG8_BAR; PG8_MMA(0, 0, At, B0); PG8_MMA(0, 1, At, B1); PG8_BAR; PG8_SCHED;
;             PG8_LDA(At, 1, 1); PG8_STAGE(PG8_SB(1, 0), b3, voffB); PG8_STAGE(PG8_SB(1, 1), b3 + hstep, voffB); PG8_STAGE(PG8_SA(1, 0), a3, voffA);
;             PG8_WAIT_V(8); PG8_WAIT_L(0); PG8_BAR; PG8_MMA(1, 0, At, B0); PG8_MMA(1, 1, At, B1); PG8_BAR; PG8_SCHED;
	s_setprio 1
	s_waitcnt lgkmcnt(0)
	v_mfma_f32_16x16x32_bf16 v[60:63], v[128:131], v[160:163], v[60:63]
	v_mfma_f32_16x16x32_bf16 v[44:47], v[136:139], v[160:163], v[44:47]
	v_mfma_f32_16x16x32_bf16 v[52:55], v[128:131], v[168:171], v[52:55]
	v_mfma_f32_16x16x32_bf16 v[36:39], v[136:139], v[168:171], v[36:39]
	v_mfma_f32_16x16x32_bf16 v[28:31], v[128:131], v[204:207], v[28:31]
	v_mfma_f32_16x16x32_bf16 v[12:15], v[136:139], v[204:207], v[12:15]
	v_mfma_f32_16x16x32_bf16 v[20:23], v[128:131], v[212:215], v[20:23]
	v_mfma_f32_16x16x32_bf16 v[4:7], v[136:139], v[212:215], v[4:7]
	v_mfma_f32_16x16x32_bf16 v[60:63], v[132:135], v[164:167], v[60:63]
	v_mfma_f32_16x16x32_bf16 v[44:47], v[140:143], v[164:167], v[44:47]
	v_mfma_f32_16x16x32_bf16 v[52:55], v[132:135], v[172:175], v[52:55]
	v_mfma_f32_16x16x32_bf16 v[36:39], v[140:143], v[172:175], v[36:39]
	v_mfma_f32_16x16x32_bf16 v[28:31], v[132:135], v[208:211], v[28:31]
	v_mfma_f32_16x16x32_bf16 v[12:15], v[140:143], v[208:211], v[12:15]
	v_mfma_f32_16x16x32_bf16 v[20:23], v[132:135], v[216:219], v[20:23]
	v_mfma_f32_16x16x32_bf16 v[4:7], v[140:143], v[216:219], v[4:7]
	s_setprio 0
	s_setprio 1
	v_mfma_f32_16x16x32_bf16 v[56:59], v[144:147], v[160:163], v[56:59]
	v_mfma_f32_16x16x32_bf16 v[40:43], v[152:155], v[160:163], v[40:43]
	v_mfma_f32_16x16x32_bf16 v[48:51], v[144:147], v[168:171], v[48:51]
	v_mfma_f32_16x16x32_bf16 v[32:35], v[152:155], v[168:171], v[32:35]
	v_mfma_f32_16x16x32_bf16 v[24:27], v[144:147], v[204:207], v[24:27]
	v_mfma_f32_16x16x32_bf16 v[8:11], v[152:155], v[204:207], v[8:11]
	v_mfma_f32_16x16x32_bf16 v[16:19], v[144:147], v[212:215], v[16:19]
	v_mfma_f32_16x16x32_bf16 v[0:3], v[152:155], v[212:215], v[0:3]
	v_mfma_f32_16x16x32_bf16 v[56:59], v[148:151], v[164:167], v[56:59]
	v_mfma_f32_16x16x32_bf16 v[40:43], v[156:159], v[164:167], v[40:43]
	v_mfma_f32_16x16x32_bf16 v[48:51], v[148:151], v[172:175], v[48:51]
	v_mfma_f32_16x16x32_bf16 v[32:35], v[156:159], v[172:175], v[32:35]
	v_mfma_f32_16x16x32_bf16 v[24:27], v[148:151], v[208:211], v[24:27]
	v_mfma_f32_16x16x32_bf16 v[8:11], v[156:159], v[208:211], v[8:11]
	v_mfma_f32_16x16x32_bf16 v[16:19], v[148:151], v[216:219], v[16:19]
	v_mfma_f32_16x16x32_bf16 v[0:3], v[156:159], v[216:219], v[0:3]
	s_setprio 0
	s_barrier
	s_add_i32 s21, 0, 0x18000
	s_add_i32 s29, 0, 0x1c000
	v_add_u32_e32 v140, s21, v187
	v_add_u32_e32 v156, s29, v187
	ds_read_b128 v[128:131], v140
	ds_read_b128 v[132:135], v140 offset:1024
	ds_read_b128 v[136:139], v140 offset:2048
	ds_read_b128 v[140:143], v140 offset:3072
	ds_read_b128 v[144:147], v156
	ds_read_b128 v[148:151], v156 offset:1024
	ds_read_b128 v[152:155], v156 offset:2048
	ds_read_b128 v[156:159], v156 offset:3072
	s_add_u32 s42, s48, 0x80000
	s_addc_u32 s43, s49, 0
	s_mov_b32 m0, s37
	s_nop 0
	global_load_lds_dwordx4 v[224:225], off
	s_mov_b32 m0, s63
	s_nop 0
	global_load_lds_dwordx4 v[238:239], off
	s_mov_b32 m0, s58
	v_lshl_add_u64 v[240:241], s[42:43], 0, v[192:193]
	ds_read_b128 v[160:163], v191 offset:32768
	ds_read_b128 v[164:167], v191 offset:33792
	ds_read_b128 v[168:171], v191 offset:34816
	ds_read_b128 v[172:175], v191 offset:35840
	ds_read_b128 v[204:207], v191 offset:36864
	ds_read_b128 v[208:211], v191 offset:37888
	ds_read_b128 v[212:215], v191 offset:38912
	ds_read_b128 v[216:219], v191 offset:39936
	global_load_lds_dwordx4 v[240:241], off
	v_lshl_add_u64 v[240:241], s[42:43], 0, v[196:197]
	s_mov_b32 m0, s59
	s_nop 0
	global_load_lds_dwordx4 v[240:241], off
	s_waitcnt vmcnt(8)
	s_waitcnt lgkmcnt(0)
	s_barrier
	s_setprio 1
	s_waitcnt lgkmcnt(0)
	v_mfma_f32_16x16x32_bf16 v[124:127], v[128:131], v[160:163], v[124:127]
	v_mfma_f32_16x16x32_bf16 v[108:111], v[136:139], v[160:163], v[108:111]
	v_mfma_f32_16x16x32_bf16 v[116:119], v[128:131], v[168:171], v[116:119]
	v_mfma_f32_16x16x32_bf16 v[100:103], v[136:139], v[168:171], v[100:103]
	v_mfma_f32_16x16x32_bf16 v[92:95], v[128:131], v[204:207], v[92:95]
	v_mfma_f32_16x16x32_bf16 v[76:79], v[136:139], v[204:207], v[76:79]
	v_mfma_f32_16x16x32_bf16 v[84:87], v[128:131], v[212:215], v[84:87]
	v_mfma_f32_16x16x32_bf16 v[68:71], v[136:139], v[212:215], v[68:71]
	v_mfma_f32_16x16x32_bf16 v[124:127], v[132:135], v[164:167], v[124:127]
	v_mfma_f32_16x16x32_bf16 v[108:111], v[140:143], v[164:167], v[108:111]
	v_mfma_f32_16x16x32_bf16 v[116:119], v[132:135], v[172:175], v[116:119]
	v_mfma_f32_16x16x32_bf16 v[100:103], v[140:143], v[172:175], v[100:103]
	v_mfma_f32_16x16x32_bf16 v[92:95], v[132:135], v[208:211], v[92:95]
	v_mfma_f32_16x16x32_bf16 v[76:79], v[140:143], v[208:211], v[76:79]
	v_mfma_f32_16x16x32_bf16 v[84:87], v[132:135], v[216:219], v[84:87]
	v_mfma_f32_16x16x32_bf16 v[68:71], v[140:143], v[216:219], v[68:71]
	s_setprio 0
	s_setprio 1
	v_mfma_f32_16x16x32_bf16 v[120:123], v[144:147], v[160:163], v[120:123]
	v_mfma_f32_16x16x32_bf16 v[104:107], v[152:155], v[160:163], v[104:107]
	v_mfma_f32_16x16x32_bf16 v[112:115], v[144:147], v[168:171], v[112:115]
	v_mfma_f32_16x16x32_bf16 v[96:99], v[152:155], v[168:171], v[96:99]
	v_mfma_f32_16x16x32_bf16 v[88:91], v[144:147], v[204:207], v[88:91]
	v_mfma_f32_16x16x32_bf16 v[72:75], v[152:155], v[204:207], v[72:75]
	v_mfma_f32_16x16x32_bf16 v[80:83], v[144:147], v[212:215], v[80:83]
	v_mfma_f32_16x16x32_bf16 v[64:67], v[152:155], v[212:215], v[64:67]
	v_mfma_f32_16x16x32_bf16 v[120:123], v[148:151], v[164:167], v[120:123]
	v_mfma_f32_16x16x32_bf16 v[104:107], v[156:159], v[164:167], v[104:107]
	v_mfma_f32_16x16x32_bf16 v[112:115], v[148:151], v[172:175], v[112:115]
	v_mfma_f32_16x16x32_bf16 v[96:99], v[156:159], v[172:175], v[96:99]
	v_mfma_f32_16x16x32_bf16 v[88:91], v[148:151], v[208:211], v[88:91]
	v_mfma_f32_16x16x32_bf16 v[72:75], v[156:159], v[208:211], v[72:75]
	v_mfma_f32_16x16x32_bf16 v[80:83], v[148:151], v[216:219], v[80:83]
	v_mfma_f32_16x16x32_bf16 v[64:67], v[156:159], v[216:219], v[64:67]
	s_setprio 0
	s_barrier
; #define PG8_STAGE(bufoff, gbase, voff) do { _Pragma("unroll") for (int _i = 0; _i < 2; ++_i) \
;         __builtin_amdgcn_global_load_lds((const unsigned*)((const char*)(gbase) + (voff)[_i]), (LAS unsigned*)(lds + (bufoff) + ldsw + _i * 8192), 16, 0, 0); } while (0)
; #define PG8_LDA(dst, b, h) do { _Pragma("unroll") for (int m = 0; m < 4; ++m) _Pragma("unroll") for (int k = 0; k < 2; ++k) dst[m][k] = *(const LAS bf16x8*)(lds + PG8_SA(b, h) + aoff + m * 2048 + k * 1024); } while (0)
; #define PG8_MMA(ai, bj, At, Bt) do { __builtin_amdgcn_s_setprio(1); _Pragma("unroll") for (int m = 0; m < 4; ++m) _Pragma("unroll") for (int n = 0; n < 2; ++n) _Pragma("unroll") for (int k = 0; k < 2; ++k) \
;         acc[ai][bj][m][n] = __builtin_amdgcn_mfma_f32_16x16x32_bf16(Bt[n][k], At[m][k], acc[ai][bj][m][n], 0, 0, 0); __builtin_amdgcn_s_setprio(0); } while (0)
; #define PG8_WAIT_V(n) asm volatile("s_waitcnt vmcnt(" #n ")" ::: "memory")
; #define PG8_WAIT_L(n) asm volatile("s_waitcnt lgkmcnt(" #n ")" ::: "memory")
; #define PG8_BAR __builtin_amdgcn_s_barrier()
; #define PG8_SCHED __builtin_amdgcn_sched_barrier(0)
; template <class Epi>
; __device__ __forceinline__ void gemm_phase(LAS unsigned char* lds, const Gemm g, const StaticOrder& S, const Epi& E, const int tid) {
;     ...
;             PG8_LDA(At, 1, 1); PG8_STAGE(PG8_SB(1, 0), b3, voffB); PG8_STAGE(PG8_SB(1, 1), b3 + hstep, voffB); PG8_STAGE(PG8_SA(1, 0), a3, voffA);
;             PG8_WAIT_V(8); PG8_WAIT_L(0); PG8_BAR; PG8_MMA(1, 0, At, B0); PG8_MMA(1, 1, At, B1); PG8_BAR; PG8_SCHED;
;         }
	s_add_i32 s21, s21, s62
	v_lshl_add_u64 v[220:221], v[220:221], 0, s[0:1]
	s_mov_b32 m0, s21
	ds_read_b128 v[160:163], v191 offset:49152
	ds_read_b128 v[164:167], v191 offset:50176
	ds_read_b128 v[168:171], v191 offset:51200
	ds_read_b128 v[172:175], v191 offset:52224
	ds_read_b128 v[204:207], v191 offset:53248
	ds_read_b128 v[208:211], v191 offset:54272
	ds_read_b128 v[212:215], v191 offset:55296
	ds_read_b128 v[216:219], v191 offset:56320
	global_load_lds_dwordx4 v[220:221], off
	s_add_i32 m0, s21, 0x2000
	s_add_u32 s42, s46, 0x80080
	v_lshl_add_u64 v[220:221], v[222:223], 0, s[0:1]
	s_addc_u32 s43, s47, 0
	s_add_i32 s21, s29, s62
	global_load_lds_dwordx4 v[220:221], off
	v_lshl_add_u64 v[220:221], s[42:43], 0, v[194:195]
	s_mov_b32 m0, s21
	s_nop 0
	global_load_lds_dwordx4 v[220:221], off
	v_lshl_add_u64 v[220:221], s[42:43], 0, v[198:199]
	s_add_i32 m0, s21, 0x2000
	s_nop 0
	global_load_lds_dwordx4 v[220:221], off
	v_lshl_add_u64 v[220:221], v[224:225], 0, s[0:1]
	s_mov_b32 m0, s94
	s_nop 0
	global_load_lds_dwordx4 v[220:221], off
	v_lshl_add_u64 v[220:221], v[238:239], 0, s[0:1]
	s_mov_b32 m0, s95
	s_nop 0
	global_load_lds_dwordx4 v[220:221], off
	s_waitcnt vmcnt(8)
	s_waitcnt lgkmcnt(0)
	s_barrier
	s_setprio 1
	s_waitcnt lgkmcnt(0)
	v_mfma_f32_16x16x32_bf16 v[60:63], v[128:131], v[160:163], v[60:63]
	v_mfma_f32_16x16x32_bf16 v[44:47], v[136:139], v[160:163], v[44:47]
	v_mfma_f32_16x16x32_bf16 v[52:55], v[128:131], v[168:171], v[52:55]
	v_mfma_f32_16x16x32_bf16 v[36:39], v[136:139], v[168:171], v[36:39]
	v_mfma_f32_16x16x32_bf16 v[28:31], v[128:131], v[204:207], v[28:31]
	v_mfma_f32_16x16x32_bf16 v[12:15], v[136:139], v[204:207], v[12:15]
	v_mfma_f32_16x16x32_bf16 v[20:23], v[128:131], v[212:215], v[20:23]
	v_mfma_f32_16x16x32_bf16 v[4:7], v[136:139], v[212:215], v[4:7]
	v_mfma_f32_16x16x32_bf16 v[60:63], v[132:135], v[164:167], v[60:63]
	v_mfma_f32_16x16x32_bf16 v[44:47], v[140:143], v[164:167], v[44:47]
	v_mfma_f32_16x16x32_bf16 v[52:55], v[132:135], v[172:175], v[52:55]
	v_mfma_f32_16x16x32_bf16 v[36:39], v[140:143], v[172:175], v[36:39]
	v_mfma_f32_16x16x32_bf16 v[28:31], v[132:135], v[208:211], v[28:31]
	v_mfma_f32_16x16x32_bf16 v[12:15], v[140:143], v[208:211], v[12:15]
	v_mfma_f32_16x16x32_bf16 v[20:23], v[132:135], v[216:219], v[20:23]
	v_mfma_f32_16x16x32_bf16 v[4:7], v[140:143], v[216:219], v[4:7]
	s_setprio 0
	s_setprio 1
	v_mfma_f32_16x16x32_bf16 v[56:59], v[144:147], v[160:163], v[56:59]
	v_mfma_f32_16x16x32_bf16 v[40:43], v[152:155], v[160:163], v[40:43]
	v_mfma_f32_16x16x32_bf16 v[48:51], v[144:147], v[168:171], v[48:51]
	v_mfma_f32_16x16x32_bf16 v[32:35], v[152:155], v[168:171], v[32:35]
	v_mfma_f32_16x16x32_bf16 v[24:27], v[144:147], v[204:207], v[24:27]
	v_mfma_f32_16x16x32_bf16 v[8:11], v[152:155], v[204:207], v[8:11]
	v_mfma_f32_16x16x32_bf16 v[16:19], v[144:147], v[212:215], v[16:19]
	v_mfma_f32_16x16x32_bf16 v[0:3], v[152:155], v[212:215], v[0:3]
	v_mfma_f32_16x16x32_bf16 v[56:59], v[148:151], v[164:167], v[56:59]
	v_mfma_f32_16x16x32_bf16 v[40:43], v[156:159], v[164:167], v[40:43]
	v_mfma_f32_16x16x32_bf16 v[48:51], v[148:151], v[172:175], v[48:51]
	v_mfma_f32_16x16x32_bf16 v[32:35], v[156:159], v[172:175], v[32:35]
	v_mfma_f32_16x16x32_bf16 v[24:27], v[148:151], v[208:211], v[24:27]
	v_mfma_f32_16x16x32_bf16 v[8:11], v[156:159], v[208:211], v[8:11]
	v_mfma_f32_16x16x32_bf16 v[16:19], v[148:151], v[216:219], v[16:19]
	v_mfma_f32_16x16x32_bf16 v[0:3], v[156:159], v[216:219], v[0:3]
	s_setprio 0
	s_barrier
	s_add_i32 s20, s20, 2
	s_add_u32 s44, s44, 0x100
	s_addc_u32 s45, s45, 0
	s_add_u32 s10, s10, 0x100
	s_addc_u32 s13, s13, 0
	s_cmp_gt_u32 s20, 29
	s_cbranch_scc0 .LBB0_214
	s_and_b64 vcc, exec, s[14:15]
	s_cbranch_vccz .LBB0_217
	s_barrier
